# index top-k threshold: value-space regula falsi search (exact termination) replacing 32-step bit bisection
# baseline (speedup 1.0000x reference)
; DI int wave_sum_i(int x) { x = row_sum16(x); return __builtin_amdgcn_readlane(x, 0) + __builtin_amdgcn_readlane(x, 16) + __builtin_amdgcn_readlane(x, 32) + __builtin_amdgcn_readlane(x, 48); }
; DI unsigned f2ord(float f) { const unsigned u = __float_as_uint(f); return (u & 0x80000000u) ? ~u : (u | 0x80000000u); }
; DI void index_unit(Frame& F, int b, int t0) {
;     ...
;         unsigned key[64];
; #pragma unroll
;         for (int i = 0; i < 64; ++i) { const int s = 64 * i + lane; key[i] = (s <= t) ? f2ord(sc[w * 4096 + s]) : 0u; }
;         unsigned res = 0u;
;         const int nreg = (t >> 6) + 1;
; #pragma unroll 1
;     ...
;             const unsigned cand = res | (1u << bit);
;             int cl = 0;
; #pragma unroll
;             for (int gq = 0; gq < 8; ++gq) if (8 * gq < nreg) {
; #pragma unroll
;                 for (int i = 8 * gq; i < 8 * gq + 8; i += 4) cl = cnt4_ge(key[i], key[i + 1], key[i + 2], key[i + 3], cand, cl); }
;             const int cnt = wave_sum_i(cl);
;             if (cnt >= 256) { res = cand; if (cnt == 256) break; }
;         }
.LBB0_337:
	s_mov_b32 s33, s82
	s_mov_b64 s[36:37], s[80:81]
	s_or_b64 exec, exec, s[0:1]
	s_cmpk_gt_u32 s34, 0x1ff
	s_cselect_b64 s[0:1], -1, 0
	s_cmpk_gt_u32 s34, 0x3ff
	s_waitcnt lgkmcnt(1)
	v_and_b32_e32 v3, 0x7fffffff, v0
	v_and_b32_e32 v2, 0x7fffffff, v1
	s_cselect_b64 s[4:5], -1, 0
	s_cmpk_gt_u32 s34, 0x5ff
	v_xor_b32_e32 v66, -1, v0
	v_pk_add_f32 v[2:3], v[2:3], 0 neg_lo:[1,1] neg_hi:[1,1]
	v_cmp_gt_i32_e32 vcc, 0, v0
	s_cselect_b64 s[6:7], -1, 0
	s_cmpk_gt_u32 s34, 0x7ff
	v_xor_b32_e32 v67, -1, v1
	v_cndmask_b32_e32 v3, v3, v66, vcc
	v_cmp_gt_i32_e32 vcc, 0, v1
	s_waitcnt lgkmcnt(0)
	v_and_b32_e32 v1, 0x7fffffff, v4
	v_and_b32_e32 v0, 0x7fffffff, v5
	s_cselect_b64 s[8:9], -1, 0
	s_cmpk_gt_u32 s34, 0x9ff
	v_cndmask_b32_e32 v2, v2, v67, vcc
	v_xor_b32_e32 v66, -1, v4
	v_pk_add_f32 v[0:1], v[0:1], 0 neg_lo:[1,1] neg_hi:[1,1]
	v_cmp_gt_i32_e32 vcc, 0, v4
	s_cselect_b64 s[10:11], -1, 0
	s_cmpk_gt_u32 s34, 0xbff
	v_xor_b32_e32 v67, -1, v5
	v_cndmask_b32_e32 v1, v1, v66, vcc
	v_cmp_gt_i32_e32 vcc, 0, v5
	s_cselect_b64 s[12:13], -1, 0
	s_cmpk_gt_u32 s34, 0xdff
	v_cndmask_b32_e32 v0, v0, v67, vcc
	s_cselect_b64 s[14:15], -1, 0
	v_max3_u32 v213, v3, v2, v1
	v_max3_u32 v213, v213, v0, v8
	v_max3_u32 v213, v213, v6, v11
	v_max3_u32 v213, v213, v7, v13
	v_max3_u32 v213, v213, v9, v15
	v_max3_u32 v213, v213, v10, v17
	v_max3_u32 v213, v213, v12, v19
	v_max3_u32 v213, v213, v14, v21
	v_max3_u32 v213, v213, v16, v23
	v_max3_u32 v213, v213, v18, v25
	v_max3_u32 v213, v213, v20, v27
	v_max3_u32 v213, v213, v22, v29
	v_max3_u32 v213, v213, v24, v31
	v_max3_u32 v213, v213, v26, v33
	v_max3_u32 v213, v213, v28, v35
	v_max3_u32 v213, v213, v30, v37
	v_max3_u32 v213, v213, v32, v39
	v_max3_u32 v213, v213, v34, v41
	v_max3_u32 v213, v213, v36, v43
	v_max3_u32 v213, v213, v38, v45
	v_max3_u32 v213, v213, v40, v47
	v_max3_u32 v213, v213, v42, v49
	v_max3_u32 v213, v213, v44, v51
	v_max3_u32 v213, v213, v46, v53
	v_max3_u32 v213, v213, v48, v55
	v_max3_u32 v213, v213, v50, v57
	v_max3_u32 v213, v213, v52, v59
	v_max3_u32 v213, v213, v54, v61
	v_max3_u32 v213, v213, v56, v63
	v_max3_u32 v213, v213, v58, v64
	v_max3_u32 v213, v213, v60, v65
	v_max_u32_e32 v213, v213, v62
	s_nop 1
	v_max_u32_dpp v213, v213, v213 quad_perm:[1,0,3,2] row_mask:0xf bank_mask:0xf bound_ctrl:1
	s_nop 1
	v_max_u32_dpp v213, v213, v213 quad_perm:[2,3,0,1] row_mask:0xf bank_mask:0xf bound_ctrl:1
	s_nop 1
	v_max_u32_dpp v213, v213, v213 row_half_mirror row_mask:0xf bank_mask:0xf bound_ctrl:1
	s_nop 1
	v_max_u32_dpp v213, v213, v213 row_mirror row_mask:0xf bank_mask:0xf bound_ctrl:1
	s_nop 1
	v_readlane_b32 s98, v213, 0
	v_readlane_b32 s100, v213, 16
	s_max_u32 s98, s98, s100
	v_readlane_b32 s100, v213, 32
	s_max_u32 s98, s98, s100
	v_readlane_b32 s100, v213, 48
	s_max_u32 s98, s98, s100
	v_mov_b32_e32 v213, s98
	s_mov_b32 s99, 1
	s_mov_b32 s101, 0
	v_mov_b32_e32 v66, 0
	v_mov_b32_e32 v4, 31
	v_bfrev_b32_e32 v5, 1
	s_branch .Lsel_count
.LBB0_338:
	s_nop 0
	v_add_u32_dpp v67, v67, v67 quad_perm:[1,0,3,2] row_mask:0xf bank_mask:0xf bound_ctrl:1
	s_nop 1
	v_add_u32_dpp v67, v67, v67 quad_perm:[2,3,0,1] row_mask:0xf bank_mask:0xf bound_ctrl:1
	s_nop 1
	v_add_u32_dpp v67, v67, v67 row_half_mirror row_mask:0xf bank_mask:0xf bound_ctrl:1
	s_nop 1
	v_add_u32_dpp v67, v67, v67 row_mirror row_mask:0xf bank_mask:0xf bound_ctrl:1
	s_nop 0
	v_readlane_b32 s16, v67, 0
	v_readlane_b32 s17, v67, 16
	s_add_i32 s16, s17, s16
	v_readlane_b32 s17, v67, 32
	s_add_i32 s16, s16, s17
	v_readlane_b32 s17, v67, 48
	s_add_i32 s35, s16, s17
	s_cmp_lg_u32 s99, 0
	s_cbranch_scc1 .Lsel_decide
	s_cmpk_lg_i32 s35, 0x100
	s_cselect_b64 s[16:17], -1, 0
	s_cmpk_lt_i32 s35, 0x100
	s_cselect_b64 vcc, -1, 0
	v_cndmask_b32_e32 v66, v5, v66, vcc
	v_add_co_u32_e32 v4, vcc, -1, v4
	s_and_b64 s[16:17], s[16:17], vcc
	s_andn2_b64 vcc, exec, s[16:17]
	s_cbranch_vccnz .LBB0_353

; DI int wave_sum_i(int x) { x = row_sum16(x); return __builtin_amdgcn_readlane(x, 0) + __builtin_amdgcn_readlane(x, 16) + __builtin_amdgcn_readlane(x, 32) + __builtin_amdgcn_readlane(x, 48); }
; DI int cnt4_ge(unsigned k0, unsigned k1, unsigned k2, unsigned k3, unsigned cand, int cl) {
;     unsigned long long m0, m1, m2, m3;
;     asm volatile("v_cmp_le_u32_e64 %1, %9, %5\n\tv_cmp_le_u32_e64 %2, %9, %6\n\tv_cmp_le_u32_e64 %3, %9, %7\n\tv_cmp_le_u32_e64 %4, %9, %8\n\t"
;                  "v_addc_co_u32_e64 %0, %1, 0, %0, %1\n\tv_addc_co_u32_e64 %0, %2, 0, %0, %2\n\tv_addc_co_u32_e64 %0, %3, 0, %0, %3\n\tv_addc_co_u32_e64 %0, %4, 0, %0, %4"
;                  : "+v"(cl), "=&s"(m0), "=&s"(m1), "=&s"(m2), "=&s"(m3) : "v"(k0), "v"(k1), "v"(k2), "v"(k3), "s"(cand));
;     return cl;
; }
; DI void index_unit(Frame& F, int b, int t0) {
;     ...
; #pragma unroll 1
;     ...
;             const unsigned cand = res | (1u << bit);
;             int cl = 0;
; #pragma unroll
;             for (int gq = 0; gq < 8; ++gq) if (8 * gq < nreg) {
; #pragma unroll
;                 for (int i = 8 * gq; i < 8 * gq + 8; i += 4) cl = cnt4_ge(key[i], key[i + 1], key[i + 2], key[i + 3], cand, cl); }
;             const int cnt = wave_sum_i(cl);
.Lsel_count:
	v_mov_b32_e32 v67, 0
	v_cndmask_b32_e64 v68, 0, 1, s[0:1]
	v_or_b32_e32 v5, v5, v66
	v_cmp_le_u32_e64 s[16:17], v5, v3
	v_cmp_le_u32_e64 s[38:39], v5, v2
	v_cmp_le_u32_e64 s[40:41], v5, v1
	v_cmp_le_u32_e64 s[42:43], v5, v0
	v_addc_co_u32_e64 v67, s[16:17], 0, v67, s[16:17]
	v_addc_co_u32_e64 v67, s[38:39], 0, v67, s[38:39]
	v_addc_co_u32_e64 v67, s[40:41], 0, v67, s[40:41]
	v_addc_co_u32_e64 v67, s[42:43], 0, v67, s[42:43]
	v_cmp_ne_u32_e64 s[82:83], 1, v68
	s_andn2_b64 vcc, exec, s[0:1]
	v_cmp_le_u32_e64 s[16:17], v5, v8
	v_cmp_le_u32_e64 s[38:39], v5, v6
	v_cmp_le_u32_e64 s[40:41], v5, v11
	v_cmp_le_u32_e64 s[42:43], v5, v7
	v_addc_co_u32_e64 v67, s[16:17], 0, v67, s[16:17]
	v_addc_co_u32_e64 v67, s[38:39], 0, v67, s[38:39]
	v_addc_co_u32_e64 v67, s[40:41], 0, v67, s[40:41]
	v_addc_co_u32_e64 v67, s[42:43], 0, v67, s[42:43]
	s_cbranch_vccz .LBB0_346
	v_cndmask_b32_e64 v68, 0, 1, s[4:5]
	v_cmp_ne_u32_e64 s[80:81], 1, v68
	s_andn2_b64 vcc, exec, s[4:5]
	s_cbranch_vccz .LBB0_347

; DI int wave_sum_i(int x) { x = row_sum16(x); return __builtin_amdgcn_readlane(x, 0) + __builtin_amdgcn_readlane(x, 16) + __builtin_amdgcn_readlane(x, 32) + __builtin_amdgcn_readlane(x, 48); }
; DI void index_unit(Frame& F, int b, int t0) {
;     ...
;         unsigned res = 0u;
;         const int nreg = (t >> 6) + 1;
; #pragma unroll 1
;     ...
;             const unsigned cand = res | (1u << bit);
;             int cl = 0;
; #pragma unroll
;             for (int gq = 0; gq < 8; ++gq) if (8 * gq < nreg) {
; #pragma unroll
;                 for (int i = 8 * gq; i < 8 * gq + 8; i += 4) cl = cnt4_ge(key[i], key[i + 1], key[i + 2], key[i + 3], cand, cl); }
;             const int cnt = wave_sum_i(cl);
;             if (cnt >= 256) { res = cand; if (cnt == 256) break; }
;         }
.Lsel_decide:
	s_add_i32 s101, s101, 1
	s_cmpk_eq_i32 s35, 0x100
	s_cbranch_scc1 .Lsel_found
	s_cmpk_gt_i32 s101, 48
	s_cbranch_scc1 .Lsel_fallback0
	s_cmp_eq_u32 s99, 1
	s_cbranch_scc0 .Lsel_step
	s_cmpk_lt_i32 s35, 0x100
	s_cbranch_scc1 .Lsel_fallback
	s_mov_b32 s99, 2
	v_bfrev_b32_e32 v208, 1
	v_add_u32_e32 v209, 1, v213
	s_add_i32 s98, s35, 0xffffff00
	v_cvt_f32_i32_e32 v210, s98
	v_mov_b32_e32 v211, 0xc3800000
	v_mov_b32_e32 v212, 0
	s_branch .Lsel_next
.Lsel_step:
	s_add_i32 s98, s35, 0xffffff00
	v_cvt_f32_i32_e32 v214, s98
	s_cmpk_gt_i32 s35, 0x100
	s_cbranch_scc0 .Lsel_below
	v_mov_b32_e32 v208, v5
	v_mov_b32_e32 v210, v214
	v_cmp_eq_u32_e64 s[44:45], 1, v212
	v_mul_f32_e32 v215, 0.5, v211
	s_nop 1
	v_cndmask_b32_e64 v211, v211, v215, s[44:45]
	v_mov_b32_e32 v212, 1
	s_branch .Lsel_next
.Lsel_below:
	v_mov_b32_e32 v209, v5
	v_mov_b32_e32 v211, v214
	v_cmp_eq_u32_e64 s[44:45], 2, v212
	v_mul_f32_e32 v215, 0.5, v210
	s_nop 1
	v_cndmask_b32_e64 v210, v210, v215, s[44:45]
	v_mov_b32_e32 v212, 2
.Lsel_next:
	v_sub_u32_e32 v214, v209, v208
	v_cmp_gt_u32_e64 s[44:45], 2, v214
	s_nop 3
	s_and_b64 vcc, exec, s[44:45]
	s_cbranch_vccnz .Lsel_adj
	s_mov_b32 s98, 0x80000000
	v_xor_b32_e32 v216, s98, v208
	v_add_u32_e32 v217, -1, v209
	v_xor_b32_e32 v217, s98, v217
	v_sub_f32_e32 v218, v210, v211
	v_rcp_f32_e32 v218, v218
	v_sub_f32_e32 v215, v217, v216
	s_nop 0
	v_mul_f32_e32 v218, v210, v218
	v_fma_f32 v215, v215, v218, v216
	v_or_b32_e32 v5, s98, v215
	v_lshrrev_b32_e32 v214, 1, v214
	v_add_u32_e32 v214, v208, v214
	v_cmp_gt_u32_e64 s[44:45], v5, v208
	v_cmp_lt_u32_e64 s[46:47], v5, v209
	s_nop 1
	s_and_b64 s[44:45], s[44:45], s[46:47]
	s_cmpk_gt_i32 s101, 24
	s_cselect_b64 s[46:47], 0, -1
	s_and_b64 s[44:45], s[44:45], s[46:47]
	v_cndmask_b32_e64 v5, v214, v5, s[44:45]
	s_branch .Lsel_count
.Lsel_found:
	v_mov_b32_e32 v66, v5
	s_mov_b32 s99, 0
	s_branch .LBB0_353
.Lsel_adj:
	v_mov_b32_e32 v66, v208
	s_mov_b32 s99, 0
	s_branch .LBB0_353
.Lsel_fallback:
	s_mov_b32 s99, 0
	v_mov_b32_e32 v4, 30
	v_mov_b32_e32 v66, 0
	s_branch .LBB0_339
.Lsel_fallback0:
	s_mov_b32 s99, 0
	v_mov_b32_e32 v4, 31
	v_mov_b32_e32 v66, 0
	s_branch .LBB0_339
